# S5 pass 2: same-wave LDS write-to-read wait dropped and dead MFMA pads removed
# speedup vs baseline: 1.0007x; 1.0007x over previous
.LBB0_873:
	v_mov_b32_e32 v224, 0x3d122279
	v_mov_b32_e32 v225, 0x3d122279
	v_mov_b32_e32 v226, 0x3f4c422a
	v_mov_b32_e32 v227, 0x3f4c422a
	v_mov_b32_e32 v228, 0xc038aa3b
	v_mov_b32_e32 v229, 0xc038aa3b
	v_mov_b32_e32 v230, 1.0
	v_mov_b32_e32 v231, 1.0
	v_cndmask_b32_e64 v93, v83, 0, s[10:11]
	v_cndmask_b32_e64 v92, v82, 0, s[10:11]
	v_cndmask_b32_e64 v91, v81, 0, s[10:11]
	v_cndmask_b32_e64 v90, v80, 0, s[10:11]
	v_add_u32_e32 v81, v139, v141
	v_add_u32_e32 v83, v139, v142
	v_mfma_f32_16x16x32_bf16 v[192:195], v[90:93], v[0:3], 0
	v_add_u32_e32 v88, v139, v143
	v_add_u32_e32 v82, s86, v140
	v_mov_b32_e32 v240, v86
	v_mov_b32_e32 v241, v87
	v_mfma_f32_16x16x32_bf16 v[196:199], v[90:93], v[4:7], 0
	v_mfma_f32_16x16x32_bf16 v[200:203], v[90:93], v[8:11], 0
	s_nop 2
	s_nop 2
	v_cndmask_b32_e64 v79, v79, 0, s[10:11]
	v_mfma_f32_16x16x32_bf16 v[204:207], v[90:93], v[12:15], 0
	v_cndmask_b32_e64 v78, v78, 0, s[10:11]
	v_cndmask_b32_e64 v77, v77, 0, s[10:11]
	v_cndmask_b32_e64 v76, v76, 0, s[10:11]
	v_mfma_f32_16x16x32_bf16 v[212:215], v[90:93], v[20:23], 0
	v_cndmask_b32_e64 v75, v75, 0, s[10:11]
	v_cndmask_b32_e64 v74, v74, 0, s[10:11]
	v_cndmask_b32_e64 v73, v73, 0, s[10:11]
	v_mfma_f32_16x16x32_bf16 v[208:211], v[90:93], v[16:19], 0
	s_nop 6
	v_mfma_f32_16x16x32_bf16 v[216:219], v[90:93], v[24:27], 0
	s_nop 6
	v_mfma_f32_16x16x32_bf16 v[220:223], v[90:93], v[28:31], 0
	v_cndmask_b32_e64 v72, v72, 0, s[10:11]
	v_cndmask_b32_e64 v71, v71, 0, s[10:11]
	v_cndmask_b32_e64 v70, v70, 0, s[10:11]
	v_mfma_f32_16x16x32_bf16 v[90:93], v[90:93], v[48:51], 0
	v_cndmask_b32_e64 v69, v69, 0, s[10:11]
	s_nop 2
	s_nop 7
	v_permlane16_swap_b32_e32 v192, v196
	v_permlane16_swap_b32_e32 v193, v197
	v_permlane16_swap_b32_e32 v194, v198
	v_permlane16_swap_b32_e32 v195, v199
	v_permlane16_swap_b32_e32 v200, v204
	v_permlane16_swap_b32_e32 v201, v205
	v_permlane16_swap_b32_e32 v202, v206
	v_permlane16_swap_b32_e32 v203, v207
	v_permlane16_swap_b32_e32 v208, v212
	v_permlane16_swap_b32_e32 v209, v213
	v_permlane16_swap_b32_e32 v210, v214
	v_permlane16_swap_b32_e32 v211, v215
	v_permlane16_swap_b32_e32 v216, v220
	v_permlane16_swap_b32_e32 v217, v221
	v_permlane16_swap_b32_e32 v218, v222
	v_permlane16_swap_b32_e32 v219, v223
	v_permlane32_swap_b32_e32 v192, v200
	v_permlane32_swap_b32_e32 v193, v201
	v_permlane32_swap_b32_e32 v194, v202
	v_permlane32_swap_b32_e32 v195, v203
	v_permlane32_swap_b32_e32 v196, v204
	v_permlane32_swap_b32_e32 v197, v205
	v_permlane32_swap_b32_e32 v198, v206
	v_permlane32_swap_b32_e32 v199, v207
	v_permlane32_swap_b32_e32 v208, v216
	v_permlane32_swap_b32_e32 v209, v217
	v_permlane32_swap_b32_e32 v210, v218
	v_permlane32_swap_b32_e32 v211, v219
	v_permlane32_swap_b32_e32 v212, v220
	v_permlane32_swap_b32_e32 v213, v221
	v_permlane32_swap_b32_e32 v214, v222
	v_permlane32_swap_b32_e32 v215, v223
	v_fma_f32 v242, -v132, v241, v192
	v_fma_f32 v243, v132, v240, v208
	v_fma_f32 v244, v128, v240, v242
	v_fma_f32 v245, v128, v241, v243
	v_cvt_pk_bf16_f32 v248, v244, v245
	ds_write_b32 v149, v248 offset:10240
	v_fma_f32 v242, -v132, v245, v193
	v_fma_f32 v243, v132, v244, v209
	v_fma_f32 v246, v128, v244, v242
	v_fma_f32 v247, v128, v245, v243
	v_cvt_pk_bf16_f32 v249, v246, v247
	ds_write_b32 v149, v249 offset:10512
	v_fma_f32 v242, -v132, v247, v194
	v_fma_f32 v243, v132, v246, v210
	v_fma_f32 v244, v128, v246, v242
	v_fma_f32 v245, v128, v247, v243
	v_cvt_pk_bf16_f32 v248, v244, v245
	ds_write_b32 v149, v248 offset:10784
	v_fma_f32 v242, -v132, v245, v195
	v_fma_f32 v243, v132, v244, v211
	v_fma_f32 v246, v128, v244, v242
	v_fma_f32 v247, v128, v245, v243
	v_cvt_pk_bf16_f32 v249, v246, v247
	ds_write_b32 v149, v249 offset:11056
	v_mfma_f32_16x16x32_bf16 v[192:195], v[76:79], v[0:3], 0
	v_mfma_f32_16x16x32_bf16 v[208:211], v[76:79], v[16:19], 0
	v_fma_f32 v242, -v132, v247, v196
	v_fma_f32 v243, v132, v246, v212
	v_fma_f32 v244, v128, v246, v242
	v_fma_f32 v245, v128, v247, v243
	v_cvt_pk_bf16_f32 v248, v244, v245
	ds_write_b32 v149, v248 offset:11328
	v_fma_f32 v242, -v132, v245, v197
	v_fma_f32 v243, v132, v244, v213
	v_fma_f32 v246, v128, v244, v242
	v_fma_f32 v247, v128, v245, v243
	v_cvt_pk_bf16_f32 v249, v246, v247
	ds_write_b32 v149, v249 offset:11600
	v_fma_f32 v242, -v132, v247, v198
	v_fma_f32 v243, v132, v246, v214
	v_fma_f32 v244, v128, v246, v242
	v_fma_f32 v245, v128, v247, v243
	v_cvt_pk_bf16_f32 v248, v244, v245
	ds_write_b32 v149, v248 offset:11872
	v_fma_f32 v242, -v132, v245, v199
	v_fma_f32 v243, v132, v244, v215
	v_fma_f32 v246, v128, v244, v242
	v_fma_f32 v247, v128, v245, v243
	v_cvt_pk_bf16_f32 v249, v246, v247
	ds_write_b32 v149, v249 offset:12144
	v_mfma_f32_16x16x32_bf16 v[196:199], v[76:79], v[4:7], 0
	v_mfma_f32_16x16x32_bf16 v[212:215], v[76:79], v[20:23], 0
	v_fma_f32 v242, -v132, v247, v200
	v_fma_f32 v243, v132, v246, v216
	v_fma_f32 v244, v128, v246, v242
	v_fma_f32 v245, v128, v247, v243
	v_cvt_pk_bf16_f32 v248, v244, v245
	ds_write_b32 v149, v248 offset:12416
	v_fma_f32 v242, -v132, v245, v201
	v_fma_f32 v243, v132, v244, v217
	v_fma_f32 v246, v128, v244, v242
	v_fma_f32 v247, v128, v245, v243
	v_cvt_pk_bf16_f32 v249, v246, v247
	ds_write_b32 v149, v249 offset:12688
	v_fma_f32 v242, -v132, v247, v202
	v_fma_f32 v243, v132, v246, v218
	v_fma_f32 v244, v128, v246, v242
	v_fma_f32 v245, v128, v247, v243
	v_cvt_pk_bf16_f32 v248, v244, v245
	ds_write_b32 v149, v248 offset:12960
	v_fma_f32 v242, -v132, v245, v203
	v_fma_f32 v243, v132, v244, v219
	v_fma_f32 v246, v128, v244, v242
	v_fma_f32 v247, v128, v245, v243
	v_cvt_pk_bf16_f32 v249, v246, v247
	ds_write_b32 v149, v249 offset:13232
	v_mfma_f32_16x16x32_bf16 v[200:203], v[76:79], v[8:11], 0
	v_mfma_f32_16x16x32_bf16 v[216:219], v[76:79], v[24:27], 0
	v_fma_f32 v242, -v132, v247, v204
	v_fma_f32 v243, v132, v246, v220
	v_fma_f32 v244, v128, v246, v242
	v_fma_f32 v245, v128, v247, v243
	v_cvt_pk_bf16_f32 v248, v244, v245
	ds_write_b32 v149, v248 offset:13504
	v_fma_f32 v242, -v132, v245, v205
	v_fma_f32 v243, v132, v244, v221
	v_fma_f32 v246, v128, v244, v242
	v_fma_f32 v247, v128, v245, v243
	v_cvt_pk_bf16_f32 v249, v246, v247
	ds_write_b32 v149, v249 offset:13776
	v_fma_f32 v242, -v132, v247, v206
	v_fma_f32 v243, v132, v246, v222
	v_fma_f32 v244, v128, v246, v242
	v_fma_f32 v245, v128, v247, v243
	v_cvt_pk_bf16_f32 v248, v244, v245
	ds_write_b32 v149, v248 offset:14048
	v_fma_f32 v242, -v132, v245, v207
	v_fma_f32 v243, v132, v244, v223
	v_fma_f32 v87, v128, v244, v242
	v_fma_f32 v86, v128, v245, v243
	v_cvt_pk_bf16_f32 v249, v87, v86
	ds_write_b32 v149, v249 offset:14320
	v_mfma_f32_16x16x32_bf16 v[204:207], v[76:79], v[12:15], 0
	v_mfma_f32_16x16x32_bf16 v[220:223], v[76:79], v[28:31], 0
	v_add_u32_e32 v80, v150, v138
	ds_read_b128 v[94:97], v80 offset:10240
	ds_read_b128 v[98:101], v80 offset:10304
	ds_read_b128 v[184:187], v80 offset:10368
	ds_read_b128 v[188:191], v80 offset:10432
	v_cndmask_b32_e64 v68, v68, 0, s[10:11]
	s_add_u32 s30, s30, 0x40000
	s_addc_u32 s31, s31, 0
	s_cmp_eq_u32 s30, 0x240000
	s_cselect_b64 s[34:35], -1, 0
	v_mov_b32_e32 v240, v87
	v_mov_b32_e32 v241, v86
	v_mfma_f32_16x16x32_bf16 v[76:79], v[76:79], v[48:51], 0
	v_permlane16_swap_b32_e32 v192, v196
	v_permlane16_swap_b32_e32 v193, v197
	v_permlane16_swap_b32_e32 v194, v198
	v_permlane16_swap_b32_e32 v195, v199
	v_permlane16_swap_b32_e32 v200, v204
	v_permlane16_swap_b32_e32 v201, v205
	v_permlane16_swap_b32_e32 v202, v206
	v_permlane16_swap_b32_e32 v203, v207
	v_permlane16_swap_b32_e32 v208, v212
	v_permlane16_swap_b32_e32 v209, v213
	v_permlane16_swap_b32_e32 v210, v214
	v_permlane16_swap_b32_e32 v211, v215
	v_permlane16_swap_b32_e32 v216, v220
	v_permlane16_swap_b32_e32 v217, v221
	v_permlane16_swap_b32_e32 v218, v222
	v_permlane16_swap_b32_e32 v219, v223
	v_permlane32_swap_b32_e32 v192, v200
	v_permlane32_swap_b32_e32 v193, v201
	v_permlane32_swap_b32_e32 v194, v202
	v_permlane32_swap_b32_e32 v195, v203
	v_permlane32_swap_b32_e32 v196, v204
	v_permlane32_swap_b32_e32 v197, v205
	v_permlane32_swap_b32_e32 v198, v206
	v_permlane32_swap_b32_e32 v199, v207
	v_permlane32_swap_b32_e32 v208, v216
	v_permlane32_swap_b32_e32 v209, v217
	v_permlane32_swap_b32_e32 v210, v218
	v_permlane32_swap_b32_e32 v211, v219
	v_permlane32_swap_b32_e32 v212, v220
	v_permlane32_swap_b32_e32 v213, v221
	v_permlane32_swap_b32_e32 v214, v222
	v_permlane32_swap_b32_e32 v215, v223
	v_fma_f32 v242, -v132, v241, v192
	v_fma_f32 v243, v132, v240, v208
	v_fma_f32 v244, v128, v240, v242
	v_fma_f32 v245, v128, v241, v243
	v_cvt_pk_bf16_f32 v248, v244, v245
	ds_write_b32 v149, v248 offset:10240
	s_waitcnt lgkmcnt(4)
	v_mfma_f32_16x16x32_bf16 v[90:93], v[94:97], v[32:35], v[90:93]
	v_fma_f32 v242, -v132, v245, v193
	v_fma_f32 v243, v132, v244, v209
	v_fma_f32 v246, v128, v244, v242
	v_fma_f32 v247, v128, v245, v243
	v_cvt_pk_bf16_f32 v249, v246, v247
	ds_write_b32 v149, v249 offset:10512
	s_waitcnt lgkmcnt(4)
	v_mfma_f32_16x16x32_bf16 v[90:93], v[98:101], v[36:39], v[90:93]
	v_fma_f32 v242, -v132, v247, v194
	v_fma_f32 v243, v132, v246, v210
	v_fma_f32 v244, v128, v246, v242
	v_fma_f32 v245, v128, v247, v243
	v_cvt_pk_bf16_f32 v248, v244, v245
	ds_write_b32 v149, v248 offset:10784
	s_waitcnt lgkmcnt(4)
	v_mfma_f32_16x16x32_bf16 v[90:93], v[184:187], v[40:43], v[90:93]
	v_fma_f32 v242, -v132, v245, v195
	v_fma_f32 v243, v132, v244, v211
	v_fma_f32 v246, v128, v244, v242
	v_fma_f32 v247, v128, v245, v243
	v_cvt_pk_bf16_f32 v249, v246, v247
	ds_write_b32 v149, v249 offset:11056
	v_mfma_f32_16x16x32_bf16 v[192:195], v[72:75], v[0:3], 0
	v_mfma_f32_16x16x32_bf16 v[208:211], v[72:75], v[16:19], 0
	s_waitcnt lgkmcnt(4)
	v_mfma_f32_16x16x32_bf16 v[90:93], v[188:191], v[44:47], v[90:93]
	v_fma_f32 v242, -v132, v247, v196
	v_fma_f32 v243, v132, v246, v212
	v_fma_f32 v244, v128, v246, v242
	v_fma_f32 v245, v128, v247, v243
	v_cvt_pk_bf16_f32 v248, v244, v245
	ds_write_b32 v149, v248 offset:11328
	v_fma_f32 v242, -v132, v245, v197
	v_fma_f32 v243, v132, v244, v213
	v_fma_f32 v246, v128, v244, v242
	v_fma_f32 v247, v128, v245, v243
	v_cvt_pk_bf16_f32 v249, v246, v247
	ds_write_b32 v149, v249 offset:11600
	v_fma_f32 v242, -v132, v247, v198
	v_fma_f32 v243, v132, v246, v214
	v_fma_f32 v244, v128, v246, v242
	v_fma_f32 v245, v128, v247, v243
	v_cvt_pk_bf16_f32 v248, v244, v245
	ds_write_b32 v149, v248 offset:11872
	v_pk_mul_f32 v[232:233], v[90:91], v[224:225]
	v_pk_mul_f32 v[234:235], v[92:93], v[224:225]
	v_pk_fma_f32 v[232:233], v[90:91], v[232:233], v[226:227]
	v_fma_f32 v242, -v132, v245, v199
	v_fma_f32 v243, v132, v244, v215
	v_fma_f32 v246, v128, v244, v242
	v_fma_f32 v247, v128, v245, v243
	v_cvt_pk_bf16_f32 v249, v246, v247
	ds_write_b32 v149, v249 offset:12144
	v_mfma_f32_16x16x32_bf16 v[196:199], v[72:75], v[4:7], 0
	v_mfma_f32_16x16x32_bf16 v[212:215], v[72:75], v[20:23], 0
	v_pk_fma_f32 v[234:235], v[92:93], v[234:235], v[226:227]
	v_pk_mul_f32 v[232:233], v[90:91], v[232:233]
	v_pk_mul_f32 v[234:235], v[92:93], v[234:235]
	v_fma_f32 v242, -v132, v247, v200
	v_fma_f32 v243, v132, v246, v216
	v_fma_f32 v244, v128, v246, v242
	v_fma_f32 v245, v128, v247, v243
	v_cvt_pk_bf16_f32 v248, v244, v245
	ds_write_b32 v149, v248 offset:12416
	v_pk_mul_f32 v[232:233], v[232:233], v[228:229]
	v_pk_mul_f32 v[234:235], v[234:235], v[228:229]
	v_exp_f32_e32 v232, v232
	v_fma_f32 v242, -v132, v245, v201
	v_fma_f32 v243, v132, v244, v217
	v_fma_f32 v246, v128, v244, v242
	v_fma_f32 v247, v128, v245, v243
	v_cvt_pk_bf16_f32 v249, v246, v247
	ds_write_b32 v149, v249 offset:12688
	v_exp_f32_e32 v233, v233
	v_exp_f32_e32 v234, v234
	v_exp_f32_e32 v235, v235
	v_fma_f32 v242, -v132, v247, v202
	v_fma_f32 v243, v132, v246, v218
	v_fma_f32 v244, v128, v246, v242
	v_fma_f32 v245, v128, v247, v243
	v_cvt_pk_bf16_f32 v248, v244, v245
	ds_write_b32 v149, v248 offset:12960
	v_pk_add_f32 v[232:233], v[232:233], v[230:231]
	v_pk_add_f32 v[234:235], v[234:235], v[230:231]
	v_rcp_f32_e32 v232, v232
	v_fma_f32 v242, -v132, v245, v203
	v_fma_f32 v243, v132, v244, v219
	v_fma_f32 v246, v128, v244, v242
	v_fma_f32 v247, v128, v245, v243
	v_cvt_pk_bf16_f32 v249, v246, v247
	ds_write_b32 v149, v249 offset:13232
	v_mfma_f32_16x16x32_bf16 v[200:203], v[72:75], v[8:11], 0
	v_mfma_f32_16x16x32_bf16 v[216:219], v[72:75], v[24:27], 0
	v_rcp_f32_e32 v233, v233
	v_rcp_f32_e32 v234, v234
	v_rcp_f32_e32 v235, v235
	v_fma_f32 v242, -v132, v247, v204
	v_fma_f32 v243, v132, v246, v220
	v_fma_f32 v244, v128, v246, v242
	v_fma_f32 v245, v128, v247, v243
	v_cvt_pk_bf16_f32 v248, v244, v245
	ds_write_b32 v149, v248 offset:13504
	v_pk_mul_f32 v[232:233], v[90:91], v[232:233]
	v_pk_mul_f32 v[234:235], v[92:93], v[234:235]
	v_cvt_pk_bf16_f32 v236, v232, v232
	v_fma_f32 v242, -v132, v245, v205
	v_fma_f32 v243, v132, v244, v221
	v_fma_f32 v246, v128, v244, v242
	v_fma_f32 v247, v128, v245, v243
	v_cvt_pk_bf16_f32 v249, v246, v247
	ds_write_b32 v149, v249 offset:13776
	v_cvt_pk_bf16_f32 v237, v233, v233
	v_cvt_pk_bf16_f32 v238, v234, v234
	v_cvt_pk_bf16_f32 v239, v235, v235
	v_fma_f32 v242, -v132, v247, v206
	v_fma_f32 v243, v132, v246, v222
	v_fma_f32 v244, v128, v246, v242
	v_fma_f32 v245, v128, v247, v243
	v_cvt_pk_bf16_f32 v248, v244, v245
	ds_write_b32 v149, v248 offset:14048
	ds_write_b16 v160, v236 offset:14592
	ds_write_b16 v160, v237 offset:14624
	ds_write_b16 v160, v238 offset:14656
	v_fma_f32 v242, -v132, v245, v207
	v_fma_f32 v243, v132, v244, v223
	v_fma_f32 v87, v128, v244, v242
	v_fma_f32 v86, v128, v245, v243
	v_cvt_pk_bf16_f32 v249, v87, v86
	ds_write_b32 v149, v249 offset:14320
	v_mfma_f32_16x16x32_bf16 v[204:207], v[72:75], v[12:15], 0
	v_mfma_f32_16x16x32_bf16 v[220:223], v[72:75], v[28:31], 0
	ds_write_b16 v161, v239 offset:14592
	ds_read_b128 v[90:93], v80 offset:10240
	ds_read_b128 v[94:97], v80 offset:10304
	ds_read_b128 v[184:187], v80 offset:10368
	ds_read_b128 v[188:191], v80 offset:10432
	v_mov_b32_e32 v240, v87
	v_mov_b32_e32 v241, v86
	v_mfma_f32_16x16x32_bf16 v[72:75], v[72:75], v[48:51], 0
	v_permlane16_swap_b32_e32 v192, v196
	v_permlane16_swap_b32_e32 v193, v197
	v_permlane16_swap_b32_e32 v194, v198
	v_permlane16_swap_b32_e32 v195, v199
	v_permlane16_swap_b32_e32 v200, v204
	v_permlane16_swap_b32_e32 v201, v205
	v_permlane16_swap_b32_e32 v202, v206
	v_permlane16_swap_b32_e32 v203, v207
	v_permlane16_swap_b32_e32 v208, v212
	v_permlane16_swap_b32_e32 v209, v213
	v_permlane16_swap_b32_e32 v210, v214
	v_permlane16_swap_b32_e32 v211, v215
	v_permlane16_swap_b32_e32 v216, v220
	v_permlane16_swap_b32_e32 v217, v221
	v_permlane16_swap_b32_e32 v218, v222
	v_permlane16_swap_b32_e32 v219, v223
	v_permlane32_swap_b32_e32 v192, v200
	v_permlane32_swap_b32_e32 v193, v201
	v_permlane32_swap_b32_e32 v194, v202
	v_permlane32_swap_b32_e32 v195, v203
	v_permlane32_swap_b32_e32 v196, v204
	v_permlane32_swap_b32_e32 v197, v205
	v_permlane32_swap_b32_e32 v198, v206
	v_permlane32_swap_b32_e32 v199, v207
	v_permlane32_swap_b32_e32 v208, v216
	v_permlane32_swap_b32_e32 v209, v217
	v_permlane32_swap_b32_e32 v210, v218
	v_permlane32_swap_b32_e32 v211, v219
	v_permlane32_swap_b32_e32 v212, v220
	v_permlane32_swap_b32_e32 v213, v221
	v_permlane32_swap_b32_e32 v214, v222
	v_permlane32_swap_b32_e32 v215, v223
	v_fma_f32 v242, -v132, v241, v192
	v_fma_f32 v243, v132, v240, v208
	v_fma_f32 v244, v128, v240, v242
	v_fma_f32 v245, v128, v241, v243
	v_cvt_pk_bf16_f32 v248, v244, v245
	ds_write_b32 v149, v248 offset:10240
	s_waitcnt lgkmcnt(4)
	v_mfma_f32_16x16x32_bf16 v[76:79], v[90:93], v[32:35], v[76:79]
	v_fma_f32 v242, -v132, v245, v193
	v_fma_f32 v243, v132, v244, v209
	v_fma_f32 v246, v128, v244, v242
	v_fma_f32 v247, v128, v245, v243
	v_cvt_pk_bf16_f32 v249, v246, v247
	ds_write_b32 v149, v249 offset:10512
	s_waitcnt lgkmcnt(4)
	v_mfma_f32_16x16x32_bf16 v[76:79], v[94:97], v[36:39], v[76:79]
	v_fma_f32 v242, -v132, v247, v194
	v_fma_f32 v243, v132, v246, v210
	v_fma_f32 v244, v128, v246, v242
	v_fma_f32 v245, v128, v247, v243
	v_cvt_pk_bf16_f32 v248, v244, v245
	ds_write_b32 v149, v248 offset:10784
	s_waitcnt lgkmcnt(4)
	v_mfma_f32_16x16x32_bf16 v[76:79], v[184:187], v[40:43], v[76:79]
	v_fma_f32 v242, -v132, v245, v195
	v_fma_f32 v243, v132, v244, v211
	v_fma_f32 v246, v128, v244, v242
	v_fma_f32 v247, v128, v245, v243
	v_cvt_pk_bf16_f32 v249, v246, v247
	ds_write_b32 v149, v249 offset:11056
	v_mfma_f32_16x16x32_bf16 v[192:195], v[68:71], v[0:3], 0
	v_mfma_f32_16x16x32_bf16 v[208:211], v[68:71], v[16:19], 0
	s_waitcnt lgkmcnt(4)
	v_mfma_f32_16x16x32_bf16 v[76:79], v[188:191], v[44:47], v[76:79]
	v_fma_f32 v242, -v132, v247, v196
	v_fma_f32 v243, v132, v246, v212
	v_fma_f32 v244, v128, v246, v242
	v_fma_f32 v245, v128, v247, v243
	v_cvt_pk_bf16_f32 v248, v244, v245
	ds_write_b32 v149, v248 offset:11328
	v_fma_f32 v242, -v132, v245, v197
	v_fma_f32 v243, v132, v244, v213
	v_fma_f32 v246, v128, v244, v242
	v_fma_f32 v247, v128, v245, v243
	v_cvt_pk_bf16_f32 v249, v246, v247
	ds_write_b32 v149, v249 offset:11600
	v_fma_f32 v242, -v132, v247, v198
	v_fma_f32 v243, v132, v246, v214
	v_fma_f32 v244, v128, v246, v242
	v_fma_f32 v245, v128, v247, v243
	v_cvt_pk_bf16_f32 v248, v244, v245
	ds_write_b32 v149, v248 offset:11872
	v_pk_mul_f32 v[232:233], v[76:77], v[224:225]
	v_pk_mul_f32 v[234:235], v[78:79], v[224:225]
	v_pk_fma_f32 v[232:233], v[76:77], v[232:233], v[226:227]
	v_fma_f32 v242, -v132, v245, v199
	v_fma_f32 v243, v132, v244, v215
	v_fma_f32 v246, v128, v244, v242
	v_fma_f32 v247, v128, v245, v243
	v_cvt_pk_bf16_f32 v249, v246, v247
	ds_write_b32 v149, v249 offset:12144
	v_mfma_f32_16x16x32_bf16 v[196:199], v[68:71], v[4:7], 0
	v_mfma_f32_16x16x32_bf16 v[212:215], v[68:71], v[20:23], 0
	v_pk_fma_f32 v[234:235], v[78:79], v[234:235], v[226:227]
	v_pk_mul_f32 v[232:233], v[76:77], v[232:233]
	v_pk_mul_f32 v[234:235], v[78:79], v[234:235]
	v_fma_f32 v242, -v132, v247, v200
	v_fma_f32 v243, v132, v246, v216
	v_fma_f32 v244, v128, v246, v242
	v_fma_f32 v245, v128, v247, v243
	v_cvt_pk_bf16_f32 v248, v244, v245
	ds_write_b32 v149, v248 offset:12416
	v_pk_mul_f32 v[232:233], v[232:233], v[228:229]
	v_pk_mul_f32 v[234:235], v[234:235], v[228:229]
	v_exp_f32_e32 v232, v232
	v_fma_f32 v242, -v132, v245, v201
	v_fma_f32 v243, v132, v244, v217
	v_fma_f32 v246, v128, v244, v242
	v_fma_f32 v247, v128, v245, v243
	v_cvt_pk_bf16_f32 v249, v246, v247
	ds_write_b32 v149, v249 offset:12688
	v_exp_f32_e32 v233, v233
	v_exp_f32_e32 v234, v234
	v_exp_f32_e32 v235, v235
	v_fma_f32 v242, -v132, v247, v202
	v_fma_f32 v243, v132, v246, v218
	v_fma_f32 v244, v128, v246, v242
	v_fma_f32 v245, v128, v247, v243
	v_cvt_pk_bf16_f32 v248, v244, v245
	ds_write_b32 v149, v248 offset:12960
	v_pk_add_f32 v[232:233], v[232:233], v[230:231]
	v_pk_add_f32 v[234:235], v[234:235], v[230:231]
	v_rcp_f32_e32 v232, v232
	v_fma_f32 v242, -v132, v245, v203
	v_fma_f32 v243, v132, v244, v219
	v_fma_f32 v246, v128, v244, v242
	v_fma_f32 v247, v128, v245, v243
	v_cvt_pk_bf16_f32 v249, v246, v247
	ds_write_b32 v149, v249 offset:13232
	v_mfma_f32_16x16x32_bf16 v[200:203], v[68:71], v[8:11], 0
	v_mfma_f32_16x16x32_bf16 v[216:219], v[68:71], v[24:27], 0
	v_rcp_f32_e32 v233, v233
	v_rcp_f32_e32 v234, v234
	v_rcp_f32_e32 v235, v235
	v_fma_f32 v242, -v132, v247, v204
	v_fma_f32 v243, v132, v246, v220
	v_fma_f32 v244, v128, v246, v242
	v_fma_f32 v245, v128, v247, v243
	v_cvt_pk_bf16_f32 v248, v244, v245
	ds_write_b32 v149, v248 offset:13504
	v_pk_mul_f32 v[232:233], v[76:77], v[232:233]
	v_pk_mul_f32 v[234:235], v[78:79], v[234:235]
	v_cvt_pk_bf16_f32 v236, v232, v232
	v_fma_f32 v242, -v132, v245, v205
	v_fma_f32 v243, v132, v244, v221
	v_fma_f32 v246, v128, v244, v242
	v_fma_f32 v247, v128, v245, v243
	v_cvt_pk_bf16_f32 v249, v246, v247
	ds_write_b32 v149, v249 offset:13776
	v_cvt_pk_bf16_f32 v237, v233, v233
	v_cvt_pk_bf16_f32 v238, v234, v234
	v_cvt_pk_bf16_f32 v239, v235, v235
	v_fma_f32 v242, -v132, v247, v206
	v_fma_f32 v243, v132, v246, v222
	v_fma_f32 v244, v128, v246, v242
	v_fma_f32 v245, v128, v247, v243
	v_cvt_pk_bf16_f32 v248, v244, v245
	ds_write_b32 v149, v248 offset:14048
	ds_write_b16 v160, v236 offset:15104
	ds_write_b16 v160, v237 offset:15136
	ds_write_b16 v160, v238 offset:15168
	v_fma_f32 v242, -v132, v245, v207
	v_fma_f32 v243, v132, v244, v223
	v_fma_f32 v110, v128, v244, v242
	v_fma_f32 v111, v128, v245, v243
	v_cvt_pk_bf16_f32 v249, v110, v111
	ds_write_b32 v149, v249 offset:14320
	v_mfma_f32_16x16x32_bf16 v[204:207], v[68:71], v[12:15], 0
	v_mfma_f32_16x16x32_bf16 v[220:223], v[68:71], v[28:31], 0
	ds_write_b16 v162, v239 offset:14592
	ds_read_b128 v[76:79], v80 offset:10240
	ds_read_b128 v[90:93], v80 offset:10304
	ds_read_b128 v[184:187], v80 offset:10368
	ds_read_b128 v[188:191], v80 offset:10432
	v_mov_b32_e32 v240, v110
	v_mov_b32_e32 v241, v111
	v_mfma_f32_16x16x32_bf16 v[68:71], v[68:71], v[48:51], 0
	v_permlane16_swap_b32_e32 v192, v196
	v_permlane16_swap_b32_e32 v193, v197
	v_permlane16_swap_b32_e32 v194, v198
	v_permlane16_swap_b32_e32 v195, v199
	v_permlane16_swap_b32_e32 v200, v204
	v_permlane16_swap_b32_e32 v201, v205
	v_permlane16_swap_b32_e32 v202, v206
	v_permlane16_swap_b32_e32 v203, v207
	v_permlane16_swap_b32_e32 v208, v212
	v_permlane16_swap_b32_e32 v209, v213
	v_permlane16_swap_b32_e32 v210, v214
	v_permlane16_swap_b32_e32 v211, v215
	v_permlane16_swap_b32_e32 v216, v220
	v_permlane16_swap_b32_e32 v217, v221
	v_permlane16_swap_b32_e32 v218, v222
	v_permlane16_swap_b32_e32 v219, v223
	v_permlane32_swap_b32_e32 v192, v200
	v_permlane32_swap_b32_e32 v193, v201
	v_permlane32_swap_b32_e32 v194, v202
	v_permlane32_swap_b32_e32 v195, v203
	v_permlane32_swap_b32_e32 v196, v204
	v_permlane32_swap_b32_e32 v197, v205
	v_permlane32_swap_b32_e32 v198, v206
	v_permlane32_swap_b32_e32 v199, v207
	v_permlane32_swap_b32_e32 v208, v216
	v_permlane32_swap_b32_e32 v209, v217
	v_permlane32_swap_b32_e32 v210, v218
	v_permlane32_swap_b32_e32 v211, v219
	v_permlane32_swap_b32_e32 v212, v220
	v_permlane32_swap_b32_e32 v213, v221
	v_permlane32_swap_b32_e32 v214, v222
	v_permlane32_swap_b32_e32 v215, v223
	v_fma_f32 v242, -v132, v241, v192
	v_fma_f32 v243, v132, v240, v208
	v_fma_f32 v244, v128, v240, v242
	v_fma_f32 v245, v128, v241, v243
	v_cvt_pk_bf16_f32 v248, v244, v245
	ds_write_b32 v149, v248 offset:10240
	s_waitcnt lgkmcnt(4)
	v_mfma_f32_16x16x32_bf16 v[72:75], v[76:79], v[32:35], v[72:75]
	v_fma_f32 v242, -v132, v245, v193
	v_fma_f32 v243, v132, v244, v209
	v_fma_f32 v246, v128, v244, v242
	v_fma_f32 v247, v128, v245, v243
	v_cvt_pk_bf16_f32 v249, v246, v247
	ds_write_b32 v149, v249 offset:10512
	s_waitcnt lgkmcnt(4)
	v_mfma_f32_16x16x32_bf16 v[72:75], v[90:93], v[36:39], v[72:75]
	v_fma_f32 v242, -v132, v247, v194
	v_fma_f32 v243, v132, v246, v210
	v_fma_f32 v244, v128, v246, v242
	v_fma_f32 v245, v128, v247, v243
	v_cvt_pk_bf16_f32 v248, v244, v245
	ds_write_b32 v149, v248 offset:10784
	s_waitcnt lgkmcnt(4)
	v_mfma_f32_16x16x32_bf16 v[72:75], v[184:187], v[40:43], v[72:75]
	v_fma_f32 v242, -v132, v245, v195
	v_fma_f32 v243, v132, v244, v211
	v_fma_f32 v246, v128, v244, v242
	v_fma_f32 v247, v128, v245, v243
	v_cvt_pk_bf16_f32 v249, v246, v247
	ds_write_b32 v149, v249 offset:11056
	s_waitcnt lgkmcnt(4)
	v_mfma_f32_16x16x32_bf16 v[72:75], v[188:191], v[44:47], v[72:75]
	v_fma_f32 v242, -v132, v247, v196
	v_fma_f32 v243, v132, v246, v212
	v_fma_f32 v244, v128, v246, v242
	v_fma_f32 v245, v128, v247, v243
	v_cvt_pk_bf16_f32 v248, v244, v245
	ds_write_b32 v149, v248 offset:11328
	v_fma_f32 v242, -v132, v245, v197
	v_fma_f32 v243, v132, v244, v213
	v_fma_f32 v246, v128, v244, v242
	v_fma_f32 v247, v128, v245, v243
	v_cvt_pk_bf16_f32 v249, v246, v247
	ds_write_b32 v149, v249 offset:11600
	v_fma_f32 v242, -v132, v247, v198
	v_fma_f32 v243, v132, v246, v214
	v_fma_f32 v244, v128, v246, v242
	v_fma_f32 v245, v128, v247, v243
	v_cvt_pk_bf16_f32 v248, v244, v245
	ds_write_b32 v149, v248 offset:11872
	v_pk_mul_f32 v[232:233], v[72:73], v[224:225]
	v_pk_mul_f32 v[234:235], v[74:75], v[224:225]
	v_pk_fma_f32 v[232:233], v[72:73], v[232:233], v[226:227]
	v_fma_f32 v242, -v132, v245, v199
	v_fma_f32 v243, v132, v244, v215
	v_fma_f32 v246, v128, v244, v242
	v_fma_f32 v247, v128, v245, v243
	v_cvt_pk_bf16_f32 v249, v246, v247
	ds_write_b32 v149, v249 offset:12144
	v_pk_fma_f32 v[234:235], v[74:75], v[234:235], v[226:227]
	v_pk_mul_f32 v[232:233], v[72:73], v[232:233]
	v_pk_mul_f32 v[234:235], v[74:75], v[234:235]
	v_fma_f32 v242, -v132, v247, v200
	v_fma_f32 v243, v132, v246, v216
	v_fma_f32 v244, v128, v246, v242
	v_fma_f32 v245, v128, v247, v243
	v_cvt_pk_bf16_f32 v248, v244, v245
	ds_write_b32 v149, v248 offset:12416
	v_pk_mul_f32 v[232:233], v[232:233], v[228:229]
	v_pk_mul_f32 v[234:235], v[234:235], v[228:229]
	v_exp_f32_e32 v232, v232
	v_fma_f32 v242, -v132, v245, v201
	v_fma_f32 v243, v132, v244, v217
	v_fma_f32 v246, v128, v244, v242
	v_fma_f32 v247, v128, v245, v243
	v_cvt_pk_bf16_f32 v249, v246, v247
	ds_write_b32 v149, v249 offset:12688
	v_exp_f32_e32 v233, v233
	v_exp_f32_e32 v234, v234
	v_exp_f32_e32 v235, v235
	v_fma_f32 v242, -v132, v247, v202
	v_fma_f32 v243, v132, v246, v218
	v_fma_f32 v244, v128, v246, v242
	v_fma_f32 v245, v128, v247, v243
	v_cvt_pk_bf16_f32 v248, v244, v245
	ds_write_b32 v149, v248 offset:12960
	v_pk_add_f32 v[232:233], v[232:233], v[230:231]
	v_pk_add_f32 v[234:235], v[234:235], v[230:231]
	v_rcp_f32_e32 v232, v232
	v_fma_f32 v242, -v132, v245, v203
	v_fma_f32 v243, v132, v244, v219
	v_fma_f32 v246, v128, v244, v242
	v_fma_f32 v247, v128, v245, v243
	v_cvt_pk_bf16_f32 v249, v246, v247
	ds_write_b32 v149, v249 offset:13232
	v_rcp_f32_e32 v233, v233
	v_rcp_f32_e32 v234, v234
	v_rcp_f32_e32 v235, v235
	v_fma_f32 v242, -v132, v247, v204
	v_fma_f32 v243, v132, v246, v220
	v_fma_f32 v244, v128, v246, v242
	v_fma_f32 v245, v128, v247, v243
	v_cvt_pk_bf16_f32 v248, v244, v245
	ds_write_b32 v149, v248 offset:13504
	v_pk_mul_f32 v[232:233], v[72:73], v[232:233]
	v_pk_mul_f32 v[234:235], v[74:75], v[234:235]
	v_cvt_pk_bf16_f32 v236, v232, v232
	v_fma_f32 v242, -v132, v245, v205
	v_fma_f32 v243, v132, v244, v221
	v_fma_f32 v246, v128, v244, v242
	v_fma_f32 v247, v128, v245, v243
	v_cvt_pk_bf16_f32 v249, v246, v247
	ds_write_b32 v149, v249 offset:13776
	v_cvt_pk_bf16_f32 v237, v233, v233
	v_cvt_pk_bf16_f32 v238, v234, v234
	v_cvt_pk_bf16_f32 v239, v235, v235
	v_fma_f32 v242, -v132, v247, v206
	v_fma_f32 v243, v132, v246, v222
	v_fma_f32 v244, v128, v246, v242
	v_fma_f32 v245, v128, v247, v243
	v_cvt_pk_bf16_f32 v248, v244, v245
	ds_write_b32 v149, v248 offset:14048
	ds_write_b16 v160, v236 offset:15616
	ds_write_b16 v160, v237 offset:15648
	ds_write_b16 v160, v238 offset:15680
	v_fma_f32 v242, -v132, v245, v207
	v_fma_f32 v243, v132, v244, v223
	v_fma_f32 v86, v128, v244, v242
	v_fma_f32 v87, v128, v245, v243
	v_cvt_pk_bf16_f32 v249, v86, v87
	ds_write_b32 v149, v249 offset:14320
	ds_write_b16 v163, v239 offset:14592
	ds_read_b128 v[72:75], v80 offset:10240
	ds_read_b128 v[76:79], v80 offset:10304
	ds_read_b128 v[184:187], v80 offset:10368
	ds_read_b128 v[188:191], v80 offset:10432
	s_waitcnt lgkmcnt(3)
	v_mfma_f32_16x16x32_bf16 v[68:71], v[72:75], v[32:35], v[68:71]
	s_waitcnt lgkmcnt(2)
	v_mfma_f32_16x16x32_bf16 v[68:71], v[76:79], v[36:39], v[68:71]
	s_waitcnt vmcnt(3)
	v_mov_b64_e32 v[82:83], v[54:55]
	v_mov_b64_e32 v[80:81], v[52:53]
	s_waitcnt lgkmcnt(1)
	v_mfma_f32_16x16x32_bf16 v[68:71], v[184:187], v[40:43], v[68:71]
	s_waitcnt lgkmcnt(0)
	v_mfma_f32_16x16x32_bf16 v[68:71], v[188:191], v[44:47], v[68:71]
	s_waitcnt vmcnt(2)
	v_mov_b64_e32 v[78:79], v[58:59]
	v_mov_b64_e32 v[76:77], v[56:57]
	s_nop 4
	v_pk_mul_f32 v[232:233], v[68:69], v[224:225]
	v_pk_mul_f32 v[234:235], v[70:71], v[224:225]
	v_pk_fma_f32 v[232:233], v[68:69], v[232:233], v[226:227]
	v_pk_fma_f32 v[234:235], v[70:71], v[234:235], v[226:227]
	v_pk_mul_f32 v[232:233], v[68:69], v[232:233]
	v_pk_mul_f32 v[234:235], v[70:71], v[234:235]
	v_pk_mul_f32 v[232:233], v[232:233], v[228:229]
	v_pk_mul_f32 v[234:235], v[234:235], v[228:229]
	v_exp_f32_e32 v232, v232
	v_exp_f32_e32 v233, v233
	v_exp_f32_e32 v234, v234
	v_exp_f32_e32 v235, v235
	v_pk_add_f32 v[232:233], v[232:233], v[230:231]
	v_pk_add_f32 v[234:235], v[234:235], v[230:231]
	v_rcp_f32_e32 v232, v232
	v_rcp_f32_e32 v233, v233
	v_rcp_f32_e32 v234, v234
	v_rcp_f32_e32 v235, v235
	v_pk_mul_f32 v[232:233], v[68:69], v[232:233]
	v_pk_mul_f32 v[234:235], v[70:71], v[234:235]
	v_cvt_pk_bf16_f32 v236, v232, v232
	v_cvt_pk_bf16_f32 v237, v233, v233
	v_cvt_pk_bf16_f32 v238, v234, v234
	v_cvt_pk_bf16_f32 v239, v235, v235
	ds_write_b16 v160, v236 offset:16128
	ds_write_b16 v160, v237 offset:16160
	ds_write_b16 v160, v238 offset:16192
	ds_write_b16 v164, v239 offset:14592
	s_waitcnt vmcnt(1)
	v_mov_b64_e32 v[74:75], v[62:63]
	v_mov_b64_e32 v[72:73], v[60:61]
	s_waitcnt lgkmcnt(0)
	s_waitcnt vmcnt(0)
	v_mov_b64_e32 v[70:71], v[66:67]
	v_mov_b64_e32 v[68:69], v[64:65]
